# same as previous with the unreachable forget-gate epilogue blocks deleted
# speedup vs baseline: 1.0151x; 1.0000x over previous
; __device__ __forceinline__ void epi_all_run(const void* Pk_, int l, int s, const f32x4 (&acc)[2][2][4][2], const pg8::Unit& u, int wr, int wc, int fr, int fq) {
;     ...
;             } else if (wc == 0 && fq == 0) {
;                 float* logf = (float*)(ws + WS_LOGF);
;                 const f32x4 fbv = *(const f32x4*)(A.fox_fb + l * 4);
; #pragma unroll
;                 for (int ai = 0; ai < 2; ++ai)
; #pragma unroll
;                     for (int m = 0; m < 4; ++m) {
;                         const int row = row0 + ai * 128 + m * 16;
;                         const f32x4 z = acc[ai][0][m][0] + fbv;
;                         f32x4 ls;
; #pragma unroll
;                         for (int j = 0; j < 4; ++j) ls[j] = fminf(z[j], 0.f) - log1pf(expf(-fabsf(z[j])));
;                         *(f32x4*)(logf + (size_t)row * 4) = ls;
.LBB0_72:
	s_andn2_b64 vcc, exec, s[50:51]
	s_lshl_b32 s50, s30, 8
	s_cbranch_vccnz .LBB0_80
	s_cmp_gt_i32 s30, 9
	s_mov_b64 s[46:47], -1
	s_cbranch_scc0 .LBB0_77
	s_cmp_eq_u32 s64, 0
	s_cselect_b64 vcc, -1, 0
	s_and_saveexec_b64 s[46:47], vcc
	s_cbranch_execz .LBB0_76
	v_and_b32_e32 v198, 15, v222
	v_lshlrev_b32_e32 v198, 2, v198
	v_bfe_u32 v199, v222, 4, 2
	ds_bpermute_b32 v190, v198, v94
	ds_bpermute_b32 v194, v198, v78
	ds_bpermute_b32 v191, v198, v95
	ds_bpermute_b32 v195, v198, v79
	ds_bpermute_b32 v192, v198, v96
	ds_bpermute_b32 v196, v198, v80
	ds_bpermute_b32 v193, v198, v97
	ds_bpermute_b32 v197, v198, v81
	v_cmp_eq_u32_e32 vcc, 1, v199
	s_waitcnt lgkmcnt(0)
	s_nop 0
	v_cndmask_b32_e32 v126, v126, v190, vcc
	v_cndmask_b32_e32 v110, v110, v194, vcc
	v_cndmask_b32_e32 v127, v127, v191, vcc
	v_cndmask_b32_e32 v111, v111, v195, vcc
	v_cndmask_b32_e32 v128, v128, v192, vcc
	v_cndmask_b32_e32 v112, v112, v196, vcc
	v_cndmask_b32_e32 v129, v129, v193, vcc
	v_cndmask_b32_e32 v113, v113, v197, vcc
	ds_bpermute_b32 v190, v198, v62
	ds_bpermute_b32 v194, v198, v46
	ds_bpermute_b32 v191, v198, v63
	ds_bpermute_b32 v195, v198, v47
	ds_bpermute_b32 v192, v198, v64
	ds_bpermute_b32 v196, v198, v48
	ds_bpermute_b32 v193, v198, v65
	ds_bpermute_b32 v197, v198, v49
	v_cmp_eq_u32_e32 vcc, 2, v199
	s_waitcnt lgkmcnt(0)
	s_nop 0
	v_cndmask_b32_e32 v126, v126, v190, vcc
	v_cndmask_b32_e32 v110, v110, v194, vcc
	v_cndmask_b32_e32 v127, v127, v191, vcc
	v_cndmask_b32_e32 v111, v111, v195, vcc
	v_cndmask_b32_e32 v128, v128, v192, vcc
	v_cndmask_b32_e32 v112, v112, v196, vcc
	v_cndmask_b32_e32 v129, v129, v193, vcc
	v_cndmask_b32_e32 v113, v113, v197, vcc
	ds_bpermute_b32 v190, v198, v30
	ds_bpermute_b32 v194, v198, v14
	ds_bpermute_b32 v191, v198, v31
	ds_bpermute_b32 v195, v198, v15
	ds_bpermute_b32 v192, v198, v32
	ds_bpermute_b32 v196, v198, v16
	ds_bpermute_b32 v193, v198, v33
	ds_bpermute_b32 v197, v198, v17
	v_cmp_eq_u32_e32 vcc, 3, v199
	s_waitcnt lgkmcnt(0)
	s_nop 0
	v_cndmask_b32_e32 v126, v126, v190, vcc
	v_cndmask_b32_e32 v110, v110, v194, vcc
	v_cndmask_b32_e32 v127, v127, v191, vcc
	v_cndmask_b32_e32 v111, v111, v195, vcc
	v_cndmask_b32_e32 v128, v128, v192, vcc
	v_cndmask_b32_e32 v112, v112, v196, vcc
	v_cndmask_b32_e32 v129, v129, v193, vcc
	v_cndmask_b32_e32 v113, v113, v197, vcc
	v_lshrrev_b32_e32 v190, 1, v199
	v_lshlrev_b32_e32 v190, 7, v190
	v_and_b32_e32 v191, 1, v199
	v_lshl_add_u32 v190, v191, 5, v190
	v_add_u32_e32 v184, v184, v190
	s_load_dwordx2 s[54:55], s[4:5], 0xb8
	s_add_u32 s52, s34, 0x200000
	s_addc_u32 s53, s35, 0
	s_lshl_b32 s78, s75, 2
	s_ashr_i32 s79, s78, 31
	s_lshl_b64 s[78:79], s[78:79], 2
	s_waitcnt lgkmcnt(0)
	s_add_u32 s54, s54, s78
	s_addc_u32 s55, s55, s79
	global_load_dwordx4 v[130:133], v0, s[54:55]
	s_mov_b32 s20, 0x3ecc95a3
	v_mov_b64_e32 v[134:135], s[20:21]
	s_mov_b32 s20, 0xbfb8aa3b
	s_mov_b32 s51, 0xb2a5705f
	s_mov_b32 s54, 0x42ce8ed0
	s_mov_b32 s55, 0xc2b17218
	s_mov_b32 s78, 0x3f2aaaab
	s_mov_b32 s84, 0x3f317218
	s_mov_b32 s86, 0xb102e308
	s_mov_b32 s80, 0x3e9b6dac
	s_mov_b32 s82, 0x3f2aaada
	s_mov_b32 s77, 0x7f800000
	s_mov_b32 s79, 0x33800000
	v_ashrrev_i32_e32 v185, 31, v184
	s_waitcnt vmcnt(0)
	v_add_f32_e32 v138, v126, v130
	v_add_f32_e32 v139, v127, v131
	v_mul_f32_e64 v136, |v138|, s20
	v_mul_f32_e64 v137, |v139|, s20
	v_fma_f32 v140, |v138|, s20, -v136
	v_rndne_f32_e32 v141, v136
	v_fma_f32 v142, |v139|, s20, -v137
	v_rndne_f32_e32 v143, v137
	v_fma_f32 v140, |v138|, s51, v140
	v_sub_f32_e32 v136, v136, v141
	v_fma_f32 v142, |v139|, s51, v142
	v_sub_f32_e32 v137, v137, v143
	v_add_f32_e32 v136, v136, v140
	v_cvt_i32_f32_e32 v141, v141
	v_add_f32_e32 v137, v137, v142
	v_exp_f32_e32 v140, v136
	v_cvt_i32_f32_e32 v143, v143
	v_exp_f32_e32 v142, v137
	v_cmp_ngt_f32_e64 vcc, |v138|, s54
	v_ldexp_f32 v140, v140, v141
	v_min_f32_e32 v136, 0, v138
	v_ldexp_f32 v141, v142, v143
	v_cndmask_b32_e32 v140, 0, v140, vcc
	v_cmp_ngt_f32_e64 vcc, |v139|, s54
	v_min_f32_e32 v137, 0, v139
	s_nop 0
	v_cndmask_b32_e32 v141, 0, v141, vcc
	v_cmp_nlt_f32_e64 vcc, |v138|, s55
	s_nop 1
	v_cndmask_b32_e32 v168, v221, v140, vcc
	v_cmp_nlt_f32_e64 vcc, |v139|, s55
	v_add_f32_e32 v142, 1.0, v168
	v_add_f32_e32 v144, -1.0, v142
	v_cndmask_b32_e32 v169, v221, v141, vcc
	v_add_f32_e32 v143, 1.0, v169
	v_frexp_mant_f32_e32 v147, v143
	v_cvt_f64_f32_e32 v[140:141], v143
	v_frexp_exp_i32_f64_e32 v140, v[140:141]
	v_cmp_gt_f32_e32 vcc, s78, v147
	v_frexp_mant_f32_e32 v145, v142
	v_cvt_f64_f32_e32 v[138:139], v142
	v_add_f32_e32 v146, -1.0, v143
	v_subbrev_co_u32_e32 v140, vcc, 0, v140, vcc
	v_sub_f32_e32 v148, v144, v142
	v_frexp_exp_i32_f64_e32 v138, v[138:139]
	v_sub_f32_e32 v139, v146, v143
	v_cmp_gt_f32_e32 vcc, s78, v145
	v_sub_f32_e32 v144, v168, v144
	v_sub_f32_e32 v146, v169, v146
	v_add_f32_e32 v141, 1.0, v148
	v_add_f32_e32 v139, 1.0, v139
	v_subbrev_co_u32_e32 v138, vcc, 0, v138, vcc
	v_add_f32_e32 v141, v144, v141
	v_add_f32_e32 v144, v146, v139
	v_sub_u32_e32 v145, 0, v138
	v_sub_u32_e32 v146, 0, v140
	v_cvt_f32_i32_e32 v139, v140
	v_cvt_f32_i32_e32 v138, v138
	v_ldexp_f32 v140, v142, v145
	v_ldexp_f32 v142, v141, v145
	v_ldexp_f32 v141, v143, v146
	v_ldexp_f32 v143, v144, v146
	v_pk_add_f32 v[144:145], v[140:141], 1.0 op_sel_hi:[1,0]
	v_pk_add_f32 v[146:147], v[140:141], -1.0 op_sel_hi:[1,0]
	v_pk_add_f32 v[148:149], v[144:145], -1.0 op_sel_hi:[1,0]
	v_pk_add_f32 v[150:151], v[146:147], 1.0 op_sel_hi:[1,0]
	v_pk_add_f32 v[148:149], v[140:141], v[148:149] neg_lo:[0,1] neg_hi:[0,1]
	v_pk_add_f32 v[140:141], v[140:141], v[150:151] neg_lo:[0,1] neg_hi:[0,1]
	v_pk_mul_f32 v[150:151], v[138:139], s[84:85] op_sel_hi:[1,0]
; __device__ __forceinline__ void epi_all_run(const void* Pk_, int l, int s, const f32x4 (&acc)[2][2][4][2], const pg8::Unit& u, int wr, int wc, int fr, int fq) {
;     ...
;                         for (int j = 0; j < 4; ++j) ls[j] = fminf(z[j], 0.f) - log1pf(expf(-fabsf(z[j])));
	v_pk_add_f32 v[148:149], v[142:143], v[148:149]
	v_pk_add_f32 v[140:141], v[142:143], v[140:141]
	v_pk_fma_f32 v[142:143], v[138:139], s[84:85], v[150:151] op_sel_hi:[1,0,1] neg_lo:[0,0,1] neg_hi:[0,0,1]
	v_pk_add_f32 v[154:155], v[144:145], v[148:149]
	v_pk_fma_f32 v[138:139], v[138:139], s[86:87], v[142:143] op_sel_hi:[1,0,1]
	v_rcp_f32_e32 v142, v154
	v_rcp_f32_e32 v143, v155
	v_pk_add_f32 v[156:157], v[146:147], v[140:141]
	v_pk_add_f32 v[144:145], v[144:145], v[154:155] neg_lo:[0,1] neg_hi:[0,1]
	v_pk_add_f32 v[146:147], v[146:147], v[156:157] neg_lo:[0,1] neg_hi:[0,1]
	v_pk_add_f32 v[144:145], v[148:149], v[144:145]
	v_pk_add_f32 v[140:141], v[140:141], v[146:147]
	v_pk_mul_f32 v[146:147], v[156:157], v[142:143]
	v_mov_b32_e32 v152, v150
	v_pk_mul_f32 v[148:149], v[154:155], v[146:147]
	v_mov_b32_e32 v160, v138
	v_pk_fma_f32 v[162:163], v[146:147], v[154:155], v[148:149] neg_lo:[0,0,1] neg_hi:[0,0,1]
	v_pk_add_f32 v[158:159], v[150:151], v[138:139]
	v_pk_fma_f32 v[162:163], v[146:147], v[144:145], v[162:163]
	v_cmp_neq_f32_e32 vcc, s77, v168
	v_pk_add_f32 v[164:165], v[148:149], v[162:163]
	s_nop 0
	v_pk_add_f32 v[166:167], v[156:157], v[164:165] neg_lo:[0,1] neg_hi:[0,1]
	v_pk_add_f32 v[148:149], v[164:165], v[148:149] neg_lo:[0,1] neg_hi:[0,1]
	v_pk_add_f32 v[156:157], v[156:157], v[166:167] neg_lo:[0,1] neg_hi:[0,1]
	v_pk_add_f32 v[148:149], v[148:149], v[162:163] neg_lo:[0,1] neg_hi:[0,1]
	v_pk_add_f32 v[156:157], v[156:157], v[164:165] neg_lo:[0,1] neg_hi:[0,1]
	s_nop 0
	v_pk_add_f32 v[140:141], v[140:141], v[156:157]
	s_nop 0
	v_pk_add_f32 v[140:141], v[148:149], v[140:141]
	s_nop 0
	v_pk_add_f32 v[148:149], v[166:167], v[140:141]
	s_nop 0
	v_pk_mul_f32 v[156:157], v[142:143], v[148:149]
	v_pk_add_f32 v[162:163], v[166:167], v[148:149] neg_lo:[0,1] neg_hi:[0,1]
	v_pk_mul_f32 v[164:165], v[154:155], v[156:157]
	v_pk_add_f32 v[140:141], v[140:141], v[162:163]
	v_pk_fma_f32 v[154:155], v[156:157], v[154:155], v[164:165] neg_lo:[0,0,1] neg_hi:[0,0,1]
	v_pk_add_f32 v[162:163], v[146:147], v[156:157]
	v_pk_fma_f32 v[144:145], v[156:157], v[144:145], v[154:155]
	v_pk_add_f32 v[146:147], v[162:163], v[146:147] neg_lo:[0,1] neg_hi:[0,1]
	v_pk_add_f32 v[154:155], v[164:165], v[144:145]
	v_pk_add_f32 v[146:147], v[156:157], v[146:147] neg_lo:[0,1] neg_hi:[0,1]
	v_pk_add_f32 v[156:157], v[154:155], v[164:165] neg_lo:[0,1] neg_hi:[0,1]
	v_pk_add_f32 v[164:165], v[148:149], v[154:155] neg_lo:[0,1] neg_hi:[0,1]
	v_pk_add_f32 v[144:145], v[156:157], v[144:145] neg_lo:[0,1] neg_hi:[0,1]
	v_pk_add_f32 v[148:149], v[148:149], v[164:165] neg_lo:[0,1] neg_hi:[0,1]
	v_mov_b32_e32 v157, v139
	v_pk_add_f32 v[148:149], v[148:149], v[154:155] neg_lo:[0,1] neg_hi:[0,1]
	v_mov_b32_e32 v154, v158
	v_pk_add_f32 v[140:141], v[140:141], v[148:149]
	v_mov_b32_e32 v155, v151
	v_pk_add_f32 v[140:141], v[144:145], v[140:141]
	s_nop 0
	v_pk_add_f32 v[140:141], v[164:165], v[140:141]
	v_mov_b32_e32 v165, v159
	v_pk_mul_f32 v[140:141], v[142:143], v[140:141]
	s_nop 0
	v_pk_add_f32 v[140:141], v[146:147], v[140:141]
	s_nop 0
	v_pk_add_f32 v[142:143], v[162:163], v[140:141]
	s_nop 0
	v_pk_add_f32 v[144:145], v[142:143], v[162:163] neg_lo:[0,1] neg_hi:[0,1]
	v_pk_mul_f32 v[148:149], v[142:143], v[142:143]
	v_pk_add_f32 v[140:141], v[140:141], v[144:145] neg_lo:[0,1] neg_hi:[0,1]
	v_pk_fma_f32 v[144:145], v[148:149], s[80:81], v[134:135] op_sel_hi:[1,0,0]
	v_ldexp_f32 v146, v142, 1
	v_ldexp_f32 v147, v143, 1
	v_pk_mul_f32 v[142:143], v[142:143], v[148:149]
	v_pk_fma_f32 v[144:145], v[148:149], v[144:145], s[82:83] op_sel_hi:[1,1,0]
	v_mov_b32_e32 v161, v147
	v_pk_mul_f32 v[142:143], v[142:143], v[144:145]
	v_ldexp_f32 v140, v140, 1
	v_pk_add_f32 v[144:145], v[146:147], v[142:143]
	v_ldexp_f32 v141, v141, 1
	v_pk_add_f32 v[146:147], v[144:145], v[146:147] neg_lo:[0,1] neg_hi:[0,1]
	v_mov_b32_e32 v153, v143
	v_pk_add_f32 v[142:143], v[142:143], v[146:147] neg_lo:[0,1] neg_hi:[0,1]
	v_pk_add_f32 v[148:149], v[152:153], v[160:161]
	v_pk_add_f32 v[146:147], v[140:141], v[142:143]
	v_mov_b32_e32 v142, v150
	v_mov_b32_e32 v140, v138
	v_pk_add_f32 v[152:153], v[142:143], v[140:141]
	v_mov_b32_e32 v140, v144
	v_mov_b32_e32 v142, v146
	v_pk_add_f32 v[140:141], v[140:141], v[142:143]
	v_pk_add_f32 v[142:143], v[144:145], v[146:147]
	v_pk_add_f32 v[140:141], v[148:149], v[140:141]
	v_mov_b32_e32 v156, v142
	v_pk_add_f32 v[148:149], v[158:159], v[142:143]
	v_pk_add_f32 v[160:161], v[154:155], v[156:157]
	v_mov_b32_e32 v162, v142
	v_mov_b32_e32 v163, v149
	v_mov_b32_e32 v164, v144
	v_pk_add_f32 v[154:155], v[160:161], v[154:155] neg_lo:[0,1] neg_hi:[0,1]
	v_pk_add_f32 v[162:163], v[162:163], v[164:165] neg_lo:[0,1] neg_hi:[0,1]
	v_pk_add_f32 v[160:161], v[158:159], v[150:151] neg_lo:[0,1] neg_hi:[0,1]
	v_pk_add_f32 v[156:157], v[156:157], v[154:155] neg_lo:[0,1] neg_hi:[0,1]
	v_mov_b32_e32 v164, v158
	v_mov_b32_e32 v165, v149
	v_mov_b32_e32 v151, v163
	v_mov_b32_e32 v155, v145
	v_pk_add_f32 v[144:145], v[142:143], v[144:145] neg_lo:[0,1] neg_hi:[0,1]
	v_pk_add_f32 v[150:151], v[164:165], v[150:151] neg_lo:[0,1] neg_hi:[0,1]
	v_pk_add_f32 v[160:161], v[138:139], v[160:161] neg_lo:[0,1] neg_hi:[0,1]
	v_pk_add_f32 v[140:141], v[140:141], v[154:155] neg_lo:[0,1] neg_hi:[0,1]
	v_pk_add_f32 v[144:145], v[146:147], v[144:145] neg_lo:[0,1] neg_hi:[0,1]
	v_mov_b32_e32 v139, v159
	v_mov_b32_e32 v147, v143
	v_pk_add_f32 v[140:141], v[152:153], v[140:141] neg_lo:[0,1] neg_hi:[0,1]
	v_pk_add_f32 v[138:139], v[138:139], v[150:151] neg_lo:[0,1] neg_hi:[0,1]
	v_pk_add_f32 v[142:143], v[146:147], v[162:163] neg_lo:[0,1] neg_hi:[0,1]
	v_pk_add_f32 v[150:151], v[156:157], v[140:141]
; __device__ __forceinline__ void epi_all_run(const void* Pk_, int l, int s, const f32x4 (&acc)[2][2][4][2], const pg8::Unit& u, int wr, int wc, int fr, int fq) {
;     ...
;                         const f32x4 z = acc[ai][0][m][0] + fbv;
;                         f32x4 ls;
; #pragma unroll
;                         for (int j = 0; j < 4; ++j) ls[j] = fminf(z[j], 0.f) - log1pf(expf(-fabsf(z[j])));
;                         *(f32x4*)(logf + (size_t)row * 4) = ls;
	v_pk_add_f32 v[146:147], v[142:143], v[138:139]
	v_mov_b32_e32 v143, v141
	v_pk_add_f32 v[140:141], v[160:161], v[142:143]
	v_mov_b32_e32 v139, v157
	v_pk_add_f32 v[140:141], v[140:141], v[138:139] neg_lo:[0,1] neg_hi:[0,1]
	v_mov_b32_e32 v142, v146
	v_mov_b32_e32 v143, v151
	v_pk_add_f32 v[142:143], v[142:143], v[140:141] neg_lo:[0,1] neg_hi:[0,1]
	v_pk_add_f32 v[140:141], v[144:145], v[140:141] neg_lo:[0,1] neg_hi:[0,1]
	v_pk_add_f32 v[138:139], v[138:139], v[142:143] neg_lo:[0,1] neg_hi:[0,1]
	s_nop 0
	v_pk_add_f32 v[138:139], v[140:141], v[138:139]
	v_pk_add_f32 v[140:141], v[150:151], v[146:147]
	s_nop 0
	v_pk_add_f32 v[142:143], v[148:149], v[140:141]
	s_nop 0
	v_pk_add_f32 v[144:145], v[142:143], v[148:149] neg_lo:[0,1] neg_hi:[0,1]
	s_nop 0
	v_pk_add_f32 v[140:141], v[140:141], v[144:145] neg_lo:[0,1] neg_hi:[0,1]
	v_add_f32_e32 v145, v129, v133
	v_pk_add_f32 v[138:139], v[138:139], v[140:141]
	v_add_f32_e32 v140, v128, v132
	v_mul_f32_e64 v141, |v140|, s20
	v_pk_add_f32 v[138:139], v[142:143], v[138:139]
	v_fma_f32 v142, |v140|, s20, -v141
	v_rndne_f32_e32 v143, v141
	v_fma_f32 v142, |v140|, s51, v142
	v_sub_f32_e32 v141, v141, v143
	v_add_f32_e32 v141, v141, v142
	v_cndmask_b32_e32 v138, v221, v138, vcc
	v_cmp_neq_f32_e32 vcc, s77, v169
	v_exp_f32_e32 v141, v141
	v_cvt_i32_f32_e32 v142, v143
	v_cndmask_b32_e32 v139, v221, v139, vcc
	v_cmp_lt_f32_e64 vcc, |v169|, s79
	s_nop 1
	v_cndmask_b32_e32 v139, v139, v169, vcc
	v_cmp_lt_f32_e64 vcc, |v168|, s79
	s_nop 1
	v_cndmask_b32_e32 v138, v138, v168, vcc
	v_pk_add_f32 v[138:139], v[136:137], v[138:139] neg_lo:[0,1] neg_hi:[0,1]
	v_ldexp_f32 v137, v141, v142
	v_cmp_ngt_f32_e64 vcc, |v140|, s54
	v_min_f32_e32 v136, 0, v140
	s_nop 0
	v_cndmask_b32_e32 v137, 0, v137, vcc
	v_cmp_nlt_f32_e64 vcc, |v140|, s55
	s_nop 1
	v_cndmask_b32_e32 v168, v221, v137, vcc
	v_add_f32_e32 v142, 1.0, v168
	v_add_f32_e32 v137, -1.0, v142
	v_sub_f32_e32 v140, v137, v142
	v_add_f32_e32 v140, 1.0, v140
	v_sub_f32_e32 v137, v168, v137
	v_add_f32_e32 v143, v137, v140
	v_mul_f32_e64 v137, |v145|, s20
	v_fma_f32 v140, |v145|, s20, -v137
	v_rndne_f32_e32 v141, v137
	v_fma_f32 v140, |v145|, s51, v140
	v_sub_f32_e32 v137, v137, v141
	v_add_f32_e32 v137, v137, v140
	v_exp_f32_e32 v146, v137
	v_cvt_i32_f32_e32 v147, v141
	v_cvt_f64_f32_e32 v[140:141], v142
	v_frexp_exp_i32_f64_e32 v148, v[140:141]
	v_cmp_ngt_f32_e64 vcc, |v145|, s54
	v_ldexp_f32 v140, v146, v147
	v_min_f32_e32 v137, 0, v145
	v_cndmask_b32_e32 v140, 0, v140, vcc
	v_cmp_nlt_f32_e64 vcc, |v145|, s55
	v_frexp_mant_f32_e32 v144, v142
	s_nop 0
	v_cndmask_b32_e32 v169, v221, v140, vcc
	v_add_f32_e32 v145, 1.0, v169
	v_add_f32_e32 v140, -1.0, v145
	v_sub_f32_e32 v141, v140, v145
	v_add_f32_e32 v141, 1.0, v141
	v_sub_f32_e32 v140, v169, v140
	v_add_f32_e32 v146, v140, v141
	v_frexp_mant_f32_e32 v147, v145
	v_cvt_f64_f32_e32 v[140:141], v145
	v_frexp_exp_i32_f64_e32 v140, v[140:141]
	v_cmp_gt_f32_e32 vcc, s78, v147
	s_nop 1
	v_subbrev_co_u32_e32 v160, vcc, 0, v140, vcc
	v_cmp_gt_f32_e32 vcc, s78, v144
	s_nop 1
	v_subbrev_co_u32_e32 v161, vcc, 0, v148, vcc
	v_sub_u32_e32 v141, 0, v161
	v_ldexp_f32 v140, v142, v141
	v_ldexp_f32 v142, v143, v141
	v_sub_u32_e32 v143, 0, v160
	v_ldexp_f32 v141, v145, v143
	v_pk_add_f32 v[144:145], v[140:141], 1.0 op_sel_hi:[1,0]
	v_ldexp_f32 v143, v146, v143
	v_pk_add_f32 v[146:147], v[144:145], -1.0 op_sel_hi:[1,0]
	v_pk_add_f32 v[152:153], v[140:141], -1.0 op_sel_hi:[1,0]
	v_pk_add_f32 v[146:147], v[140:141], v[146:147] neg_lo:[0,1] neg_hi:[0,1]
	v_pk_add_f32 v[154:155], v[152:153], 1.0 op_sel_hi:[1,0]
	v_pk_add_f32 v[146:147], v[142:143], v[146:147]
	v_pk_add_f32 v[140:141], v[140:141], v[154:155] neg_lo:[0,1] neg_hi:[0,1]
	v_pk_add_f32 v[148:149], v[144:145], v[146:147]
	v_pk_add_f32 v[140:141], v[142:143], v[140:141]
	v_rcp_f32_e32 v150, v148
	v_rcp_f32_e32 v151, v149
	v_pk_add_f32 v[142:143], v[152:153], v[140:141]
	v_pk_add_f32 v[144:145], v[144:145], v[148:149] neg_lo:[0,1] neg_hi:[0,1]
	v_pk_add_f32 v[152:153], v[152:153], v[142:143] neg_lo:[0,1] neg_hi:[0,1]
	v_pk_add_f32 v[144:145], v[146:147], v[144:145]
	v_pk_mul_f32 v[146:147], v[142:143], v[150:151]
	v_pk_add_f32 v[140:141], v[140:141], v[152:153]
	v_pk_mul_f32 v[152:153], v[148:149], v[146:147]
	v_cmp_neq_f32_e32 vcc, s77, v168
	v_pk_fma_f32 v[154:155], v[146:147], v[148:149], v[152:153] neg_lo:[0,0,1] neg_hi:[0,0,1]
	s_nop 0
	v_pk_fma_f32 v[154:155], v[146:147], v[144:145], v[154:155]
	s_nop 0
	v_pk_add_f32 v[156:157], v[152:153], v[154:155]
	s_nop 0
	v_pk_add_f32 v[158:159], v[142:143], v[156:157] neg_lo:[0,1] neg_hi:[0,1]
	v_pk_add_f32 v[152:153], v[156:157], v[152:153] neg_lo:[0,1] neg_hi:[0,1]
	v_pk_add_f32 v[142:143], v[142:143], v[158:159] neg_lo:[0,1] neg_hi:[0,1]
	s_nop 0
	v_pk_add_f32 v[142:143], v[142:143], v[156:157] neg_lo:[0,1] neg_hi:[0,1]
	s_nop 0
	v_pk_add_f32 v[140:141], v[140:141], v[142:143]
	v_pk_add_f32 v[142:143], v[152:153], v[154:155] neg_lo:[0,1] neg_hi:[0,1]
	s_nop 0
	v_pk_add_f32 v[140:141], v[142:143], v[140:141]
	s_nop 0
	v_pk_add_f32 v[142:143], v[158:159], v[140:141]
	s_nop 0
	v_pk_mul_f32 v[152:153], v[150:151], v[142:143]
	s_nop 0
	v_pk_mul_f32 v[154:155], v[148:149], v[152:153]
	s_nop 0
	v_pk_fma_f32 v[148:149], v[152:153], v[148:149], v[154:155] neg_lo:[0,0,1] neg_hi:[0,0,1]
	s_nop 0
	v_pk_fma_f32 v[144:145], v[152:153], v[144:145], v[148:149]
	v_pk_add_f32 v[148:149], v[158:159], v[142:143] neg_lo:[0,1] neg_hi:[0,1]
	s_nop 0
	v_pk_add_f32 v[140:141], v[140:141], v[148:149]
	v_pk_add_f32 v[148:149], v[154:155], v[144:145]
	s_nop 0
	v_pk_add_f32 v[156:157], v[142:143], v[148:149] neg_lo:[0,1] neg_hi:[0,1]
; __device__ __forceinline__ void epi_all_run(const void* Pk_, int l, int s, const f32x4 (&acc)[2][2][4][2], const pg8::Unit& u, int wr, int wc, int fr, int fq) {
;     ...
;                         const f32x4 z = acc[ai][0][m][0] + fbv;
;                         f32x4 ls;
; #pragma unroll
;                         for (int j = 0; j < 4; ++j) ls[j] = fminf(z[j], 0.f) - log1pf(expf(-fabsf(z[j])));
;                         *(f32x4*)(logf + (size_t)row * 4) = ls;
	v_pk_add_f32 v[154:155], v[148:149], v[154:155] neg_lo:[0,1] neg_hi:[0,1]
	v_pk_add_f32 v[142:143], v[142:143], v[156:157] neg_lo:[0,1] neg_hi:[0,1]
	s_nop 0
	v_pk_add_f32 v[142:143], v[142:143], v[148:149] neg_lo:[0,1] neg_hi:[0,1]
	s_nop 0
	v_pk_add_f32 v[140:141], v[140:141], v[142:143]
	v_pk_add_f32 v[142:143], v[154:155], v[144:145] neg_lo:[0,1] neg_hi:[0,1]
	s_nop 0
	v_pk_add_f32 v[140:141], v[142:143], v[140:141]
	v_pk_add_f32 v[142:143], v[146:147], v[152:153]
	v_pk_add_f32 v[140:141], v[156:157], v[140:141]
	v_pk_add_f32 v[144:145], v[142:143], v[146:147] neg_lo:[0,1] neg_hi:[0,1]
	v_pk_mul_f32 v[140:141], v[150:151], v[140:141]
	v_pk_add_f32 v[144:145], v[152:153], v[144:145] neg_lo:[0,1] neg_hi:[0,1]
	v_cvt_f32_i32_e32 v147, v160
	v_pk_add_f32 v[140:141], v[144:145], v[140:141]
	v_cvt_f32_i32_e32 v146, v161
	v_pk_add_f32 v[144:145], v[142:143], v[140:141]
	v_pk_mul_f32 v[152:153], v[146:147], s[84:85] op_sel_hi:[1,0]
	v_pk_mul_f32 v[148:149], v[144:145], v[144:145]
	v_pk_add_f32 v[142:143], v[144:145], v[142:143] neg_lo:[0,1] neg_hi:[0,1]
	v_pk_fma_f32 v[150:151], v[148:149], s[80:81], v[134:135] op_sel_hi:[1,0,0]
	v_pk_add_f32 v[140:141], v[140:141], v[142:143] neg_lo:[0,1] neg_hi:[0,1]
	v_ldexp_f32 v142, v144, 1
	v_pk_fma_f32 v[150:151], v[148:149], v[150:151], s[82:83] op_sel_hi:[1,1,0]
	v_ldexp_f32 v143, v145, 1
	v_pk_mul_f32 v[144:145], v[144:145], v[148:149]
	v_pk_fma_f32 v[154:155], v[146:147], s[84:85], v[152:153] op_sel_hi:[1,0,1] neg_lo:[0,0,1] neg_hi:[0,0,1]
	v_pk_mul_f32 v[144:145], v[144:145], v[150:151]
	v_mov_b32_e32 v157, v143
	v_pk_add_f32 v[148:149], v[142:143], v[144:145]
	v_ldexp_f32 v140, v140, 1
	v_pk_add_f32 v[142:143], v[148:149], v[142:143] neg_lo:[0,1] neg_hi:[0,1]
	v_pk_fma_f32 v[146:147], v[146:147], s[86:87], v[154:155] op_sel_hi:[1,0,1]
	v_ldexp_f32 v141, v141, 1
	v_pk_add_f32 v[142:143], v[144:145], v[142:143] neg_lo:[0,1] neg_hi:[0,1]
	v_mov_b32_e32 v150, v152
	v_mov_b32_e32 v151, v145
	v_mov_b32_e32 v156, v146
	v_pk_add_f32 v[144:145], v[140:141], v[142:143]
	v_mov_b32_e32 v142, v152
	v_mov_b32_e32 v140, v146
	v_pk_add_f32 v[150:151], v[150:151], v[156:157]
	v_pk_add_f32 v[156:157], v[142:143], v[140:141]
	v_mov_b32_e32 v140, v148
	v_mov_b32_e32 v142, v144
	v_pk_add_f32 v[154:155], v[152:153], v[146:147]
	v_pk_add_f32 v[140:141], v[140:141], v[142:143]
	v_pk_add_f32 v[142:143], v[148:149], v[144:145]
	v_mov_b32_e32 v158, v154
	v_mov_b32_e32 v159, v153
	v_mov_b32_e32 v160, v142
	v_mov_b32_e32 v161, v147
	v_pk_add_f32 v[140:141], v[150:151], v[140:141]
	v_pk_add_f32 v[150:151], v[154:155], v[142:143]
	v_pk_add_f32 v[162:163], v[158:159], v[160:161]
	v_mov_b32_e32 v164, v142
	v_mov_b32_e32 v165, v151
	v_mov_b32_e32 v166, v148
	v_mov_b32_e32 v167, v155
	v_pk_add_f32 v[158:159], v[162:163], v[158:159] neg_lo:[0,1] neg_hi:[0,1]
	v_pk_add_f32 v[164:165], v[164:165], v[166:167] neg_lo:[0,1] neg_hi:[0,1]
	v_pk_add_f32 v[162:163], v[154:155], v[152:153] neg_lo:[0,1] neg_hi:[0,1]
	v_pk_add_f32 v[160:161], v[160:161], v[158:159] neg_lo:[0,1] neg_hi:[0,1]
	v_mov_b32_e32 v166, v154
	v_mov_b32_e32 v167, v151
	v_mov_b32_e32 v153, v165
	v_mov_b32_e32 v159, v149
	v_pk_add_f32 v[148:149], v[142:143], v[148:149] neg_lo:[0,1] neg_hi:[0,1]
	v_pk_add_f32 v[152:153], v[166:167], v[152:153] neg_lo:[0,1] neg_hi:[0,1]
	v_pk_add_f32 v[162:163], v[146:147], v[162:163] neg_lo:[0,1] neg_hi:[0,1]
	v_pk_add_f32 v[140:141], v[140:141], v[158:159] neg_lo:[0,1] neg_hi:[0,1]
	v_pk_add_f32 v[148:149], v[144:145], v[148:149] neg_lo:[0,1] neg_hi:[0,1]
	v_mov_b32_e32 v147, v155
	v_mov_b32_e32 v145, v143
	v_pk_add_f32 v[140:141], v[156:157], v[140:141] neg_lo:[0,1] neg_hi:[0,1]
	v_pk_add_f32 v[146:147], v[146:147], v[152:153] neg_lo:[0,1] neg_hi:[0,1]
	v_pk_add_f32 v[142:143], v[144:145], v[164:165] neg_lo:[0,1] neg_hi:[0,1]
	v_pk_add_f32 v[152:153], v[160:161], v[140:141]
	v_pk_add_f32 v[144:145], v[142:143], v[146:147]
	v_mov_b32_e32 v143, v141
	v_pk_add_f32 v[140:141], v[162:163], v[142:143]
	v_mov_b32_e32 v147, v161
	v_pk_add_f32 v[140:141], v[140:141], v[146:147] neg_lo:[0,1] neg_hi:[0,1]
	v_mov_b32_e32 v142, v144
	v_mov_b32_e32 v143, v153
	v_pk_add_f32 v[142:143], v[142:143], v[140:141] neg_lo:[0,1] neg_hi:[0,1]
	v_pk_add_f32 v[140:141], v[148:149], v[140:141] neg_lo:[0,1] neg_hi:[0,1]
	v_pk_add_f32 v[142:143], v[146:147], v[142:143] neg_lo:[0,1] neg_hi:[0,1]
	s_nop 0
	v_pk_add_f32 v[140:141], v[140:141], v[142:143]
	v_pk_add_f32 v[142:143], v[152:153], v[144:145]
	s_nop 0
	v_pk_add_f32 v[144:145], v[150:151], v[142:143]
	s_nop 0
	v_pk_add_f32 v[146:147], v[144:145], v[150:151] neg_lo:[0,1] neg_hi:[0,1]
	s_nop 0
	v_pk_add_f32 v[142:143], v[142:143], v[146:147] neg_lo:[0,1] neg_hi:[0,1]
	s_nop 0
	v_pk_add_f32 v[140:141], v[140:141], v[142:143]
	v_add_f32_e32 v142, v110, v130
	v_pk_add_f32 v[140:141], v[144:145], v[140:141]
	v_add_f32_e32 v145, v111, v131
	v_cndmask_b32_e32 v140, v221, v140, vcc
	v_cmp_neq_f32_e32 vcc, s77, v169
	s_nop 1
	v_cndmask_b32_e32 v141, v221, v141, vcc
	v_cmp_lt_f32_e64 vcc, |v169|, s79
	s_nop 1
	v_cndmask_b32_e32 v141, v141, v169, vcc
	v_cmp_lt_f32_e64 vcc, |v168|, s79
	s_nop 1
	v_cndmask_b32_e32 v140, v140, v168, vcc
	v_pk_add_f32 v[140:141], v[136:137], v[140:141] neg_lo:[0,1] neg_hi:[0,1]
	v_mul_f32_e64 v136, |v142|, s20
	v_fma_f32 v137, |v142|, s20, -v136
	v_rndne_f32_e32 v143, v136
	v_fma_f32 v137, |v142|, s51, v137
	v_sub_f32_e32 v136, v136, v143
	v_add_f32_e32 v136, v136, v137
	v_exp_f32_e32 v144, v136
	v_cvt_i32_f32_e32 v143, v143
	v_lshl_add_u64 v[136:137], v[184:185], 4, s[52:53]
	global_store_dwordx4 v[136:137], v[138:141], off
	v_cmp_ngt_f32_e64 vcc, |v142|, s54
	s_nop 0
	v_ldexp_f32 v139, v144, v143
; __device__ __forceinline__ void epi_all_run(const void* Pk_, int l, int s, const f32x4 (&acc)[2][2][4][2], const pg8::Unit& u, int wr, int wc, int fr, int fq) {
;     ...
;                         for (int j = 0; j < 4; ++j) ls[j] = fminf(z[j], 0.f) - log1pf(expf(-fabsf(z[j])));
	v_cndmask_b32_e32 v139, 0, v139, vcc
	v_cmp_nlt_f32_e64 vcc, |v142|, s55
	v_min_f32_e32 v138, 0, v142
	s_nop 0
	v_cndmask_b32_e32 v168, v221, v139, vcc
	v_add_f32_e32 v142, 1.0, v168
	v_add_f32_e32 v139, -1.0, v142
	v_sub_f32_e32 v140, v139, v142
	v_add_f32_e32 v140, 1.0, v140
	v_sub_f32_e32 v139, v168, v139
	v_add_f32_e32 v143, v139, v140
	v_mul_f32_e64 v139, |v145|, s20
	v_fma_f32 v140, |v145|, s20, -v139
	v_rndne_f32_e32 v141, v139
	v_fma_f32 v140, |v145|, s51, v140
	v_sub_f32_e32 v139, v139, v141
	v_add_f32_e32 v139, v139, v140
	v_exp_f32_e32 v146, v139
	v_cvt_i32_f32_e32 v147, v141
	v_cvt_f64_f32_e32 v[140:141], v142
	v_frexp_exp_i32_f64_e32 v148, v[140:141]
	v_cmp_ngt_f32_e64 vcc, |v145|, s54
	v_ldexp_f32 v140, v146, v147
	v_min_f32_e32 v139, 0, v145
	v_cndmask_b32_e32 v140, 0, v140, vcc
	v_cmp_nlt_f32_e64 vcc, |v145|, s55
	v_frexp_mant_f32_e32 v144, v142
	s_nop 0
	v_cndmask_b32_e32 v169, v221, v140, vcc
	v_add_f32_e32 v145, 1.0, v169
	v_add_f32_e32 v140, -1.0, v145
	v_sub_f32_e32 v141, v140, v145
	v_add_f32_e32 v141, 1.0, v141
	v_sub_f32_e32 v140, v169, v140
	v_add_f32_e32 v146, v140, v141
	v_frexp_mant_f32_e32 v147, v145
	v_cvt_f64_f32_e32 v[140:141], v145
	v_frexp_exp_i32_f64_e32 v140, v[140:141]
	v_cmp_gt_f32_e32 vcc, s78, v147
	s_nop 1
	v_subbrev_co_u32_e32 v160, vcc, 0, v140, vcc
	v_cmp_gt_f32_e32 vcc, s78, v144
	s_nop 1
	v_subbrev_co_u32_e32 v161, vcc, 0, v148, vcc
	v_sub_u32_e32 v141, 0, v161
	v_ldexp_f32 v140, v142, v141
	v_ldexp_f32 v142, v143, v141
	v_sub_u32_e32 v143, 0, v160
	v_ldexp_f32 v141, v145, v143
	v_pk_add_f32 v[144:145], v[140:141], 1.0 op_sel_hi:[1,0]
	v_ldexp_f32 v143, v146, v143
	v_pk_add_f32 v[146:147], v[144:145], -1.0 op_sel_hi:[1,0]
	v_pk_add_f32 v[152:153], v[140:141], -1.0 op_sel_hi:[1,0]
	v_pk_add_f32 v[146:147], v[140:141], v[146:147] neg_lo:[0,1] neg_hi:[0,1]
	v_pk_add_f32 v[154:155], v[152:153], 1.0 op_sel_hi:[1,0]
	v_pk_add_f32 v[146:147], v[142:143], v[146:147]
	v_pk_add_f32 v[140:141], v[140:141], v[154:155] neg_lo:[0,1] neg_hi:[0,1]
	v_pk_add_f32 v[148:149], v[144:145], v[146:147]
	v_pk_add_f32 v[140:141], v[142:143], v[140:141]
	v_rcp_f32_e32 v150, v148
	v_rcp_f32_e32 v151, v149
	v_pk_add_f32 v[142:143], v[152:153], v[140:141]
	v_pk_add_f32 v[144:145], v[144:145], v[148:149] neg_lo:[0,1] neg_hi:[0,1]
	v_pk_add_f32 v[152:153], v[152:153], v[142:143] neg_lo:[0,1] neg_hi:[0,1]
	v_pk_add_f32 v[144:145], v[146:147], v[144:145]
	v_pk_mul_f32 v[146:147], v[142:143], v[150:151]
	v_pk_add_f32 v[140:141], v[140:141], v[152:153]
	v_pk_mul_f32 v[152:153], v[148:149], v[146:147]
	v_cmp_neq_f32_e32 vcc, s77, v168
	v_pk_fma_f32 v[154:155], v[146:147], v[148:149], v[152:153] neg_lo:[0,0,1] neg_hi:[0,0,1]
	s_nop 0
	v_pk_fma_f32 v[154:155], v[146:147], v[144:145], v[154:155]
	s_nop 0
	v_pk_add_f32 v[156:157], v[152:153], v[154:155]
	s_nop 0
	v_pk_add_f32 v[158:159], v[142:143], v[156:157] neg_lo:[0,1] neg_hi:[0,1]
	v_pk_add_f32 v[152:153], v[156:157], v[152:153] neg_lo:[0,1] neg_hi:[0,1]
	v_pk_add_f32 v[142:143], v[142:143], v[158:159] neg_lo:[0,1] neg_hi:[0,1]
	s_nop 0
	v_pk_add_f32 v[142:143], v[142:143], v[156:157] neg_lo:[0,1] neg_hi:[0,1]
	s_nop 0
	v_pk_add_f32 v[140:141], v[140:141], v[142:143]
	v_pk_add_f32 v[142:143], v[152:153], v[154:155] neg_lo:[0,1] neg_hi:[0,1]
	s_nop 0
	v_pk_add_f32 v[140:141], v[142:143], v[140:141]
	s_nop 0
	v_pk_add_f32 v[142:143], v[158:159], v[140:141]
	s_nop 0
	v_pk_mul_f32 v[152:153], v[150:151], v[142:143]
	s_nop 0
	v_pk_mul_f32 v[154:155], v[148:149], v[152:153]
	s_nop 0
	v_pk_fma_f32 v[148:149], v[152:153], v[148:149], v[154:155] neg_lo:[0,0,1] neg_hi:[0,0,1]
	s_nop 0
	v_pk_fma_f32 v[144:145], v[152:153], v[144:145], v[148:149]
	v_pk_add_f32 v[148:149], v[158:159], v[142:143] neg_lo:[0,1] neg_hi:[0,1]
	s_nop 0
	v_pk_add_f32 v[140:141], v[140:141], v[148:149]
	v_pk_add_f32 v[148:149], v[154:155], v[144:145]
	s_nop 0
	v_pk_add_f32 v[156:157], v[142:143], v[148:149] neg_lo:[0,1] neg_hi:[0,1]
	v_pk_add_f32 v[154:155], v[148:149], v[154:155] neg_lo:[0,1] neg_hi:[0,1]
	v_pk_add_f32 v[142:143], v[142:143], v[156:157] neg_lo:[0,1] neg_hi:[0,1]
	s_nop 0
	v_pk_add_f32 v[142:143], v[142:143], v[148:149] neg_lo:[0,1] neg_hi:[0,1]
	s_nop 0
	v_pk_add_f32 v[140:141], v[140:141], v[142:143]
	v_pk_add_f32 v[142:143], v[154:155], v[144:145] neg_lo:[0,1] neg_hi:[0,1]
	s_nop 0
	v_pk_add_f32 v[140:141], v[142:143], v[140:141]
	v_pk_add_f32 v[142:143], v[146:147], v[152:153]
	v_pk_add_f32 v[140:141], v[156:157], v[140:141]
	v_pk_add_f32 v[144:145], v[142:143], v[146:147] neg_lo:[0,1] neg_hi:[0,1]
	v_pk_mul_f32 v[140:141], v[150:151], v[140:141]
	v_pk_add_f32 v[144:145], v[152:153], v[144:145] neg_lo:[0,1] neg_hi:[0,1]
	v_cvt_f32_i32_e32 v147, v160
	v_pk_add_f32 v[140:141], v[144:145], v[140:141]
	v_cvt_f32_i32_e32 v146, v161
	v_pk_add_f32 v[144:145], v[142:143], v[140:141]
	v_pk_mul_f32 v[152:153], v[146:147], s[84:85] op_sel_hi:[1,0]
	v_pk_mul_f32 v[148:149], v[144:145], v[144:145]
	v_pk_add_f32 v[142:143], v[144:145], v[142:143] neg_lo:[0,1] neg_hi:[0,1]
	v_pk_fma_f32 v[150:151], v[148:149], s[80:81], v[134:135] op_sel_hi:[1,0,0]
	v_pk_add_f32 v[140:141], v[140:141], v[142:143] neg_lo:[0,1] neg_hi:[0,1]
	v_ldexp_f32 v142, v144, 1
	v_pk_fma_f32 v[150:151], v[148:149], v[150:151], s[82:83] op_sel_hi:[1,1,0]
	v_ldexp_f32 v143, v145, 1
	v_pk_mul_f32 v[144:145], v[144:145], v[148:149]
	v_pk_fma_f32 v[154:155], v[146:147], s[84:85], v[152:153] op_sel_hi:[1,0,1] neg_lo:[0,0,1] neg_hi:[0,0,1]
	v_pk_mul_f32 v[144:145], v[144:145], v[150:151]
	v_mov_b32_e32 v157, v143
	v_pk_add_f32 v[148:149], v[142:143], v[144:145]
	v_ldexp_f32 v140, v140, 1
	v_pk_add_f32 v[142:143], v[148:149], v[142:143] neg_lo:[0,1] neg_hi:[0,1]
; __device__ __forceinline__ void epi_all_run(const void* Pk_, int l, int s, const f32x4 (&acc)[2][2][4][2], const pg8::Unit& u, int wr, int wc, int fr, int fq) {
;     ...
;                         const f32x4 z = acc[ai][0][m][0] + fbv;
;                         f32x4 ls;
; #pragma unroll
;                         for (int j = 0; j < 4; ++j) ls[j] = fminf(z[j], 0.f) - log1pf(expf(-fabsf(z[j])));
;                         *(f32x4*)(logf + (size_t)row * 4) = ls;
	v_pk_fma_f32 v[146:147], v[146:147], s[86:87], v[154:155] op_sel_hi:[1,0,1]
	v_ldexp_f32 v141, v141, 1
	v_pk_add_f32 v[142:143], v[144:145], v[142:143] neg_lo:[0,1] neg_hi:[0,1]
	v_mov_b32_e32 v150, v152
	v_mov_b32_e32 v151, v145
	v_mov_b32_e32 v156, v146
	v_pk_add_f32 v[144:145], v[140:141], v[142:143]
	v_mov_b32_e32 v142, v152
	v_mov_b32_e32 v140, v146
	v_pk_add_f32 v[150:151], v[150:151], v[156:157]
	v_pk_add_f32 v[156:157], v[142:143], v[140:141]
	v_mov_b32_e32 v140, v148
	v_mov_b32_e32 v142, v144
	v_pk_add_f32 v[154:155], v[152:153], v[146:147]
	v_pk_add_f32 v[140:141], v[140:141], v[142:143]
	v_pk_add_f32 v[142:143], v[148:149], v[144:145]
	v_mov_b32_e32 v158, v154
	v_mov_b32_e32 v159, v153
	v_mov_b32_e32 v160, v142
	v_mov_b32_e32 v161, v147
	v_pk_add_f32 v[140:141], v[150:151], v[140:141]
	v_pk_add_f32 v[150:151], v[154:155], v[142:143]
	v_pk_add_f32 v[162:163], v[158:159], v[160:161]
	v_mov_b32_e32 v164, v142
	v_mov_b32_e32 v165, v151
	v_mov_b32_e32 v166, v148
	v_mov_b32_e32 v167, v155
	v_pk_add_f32 v[158:159], v[162:163], v[158:159] neg_lo:[0,1] neg_hi:[0,1]
	v_pk_add_f32 v[164:165], v[164:165], v[166:167] neg_lo:[0,1] neg_hi:[0,1]
	v_pk_add_f32 v[162:163], v[154:155], v[152:153] neg_lo:[0,1] neg_hi:[0,1]
	v_pk_add_f32 v[160:161], v[160:161], v[158:159] neg_lo:[0,1] neg_hi:[0,1]
	v_mov_b32_e32 v166, v154
	v_mov_b32_e32 v167, v151
	v_mov_b32_e32 v153, v165
	v_mov_b32_e32 v159, v149
	v_pk_add_f32 v[148:149], v[142:143], v[148:149] neg_lo:[0,1] neg_hi:[0,1]
	v_pk_add_f32 v[152:153], v[166:167], v[152:153] neg_lo:[0,1] neg_hi:[0,1]
	v_pk_add_f32 v[162:163], v[146:147], v[162:163] neg_lo:[0,1] neg_hi:[0,1]
	v_pk_add_f32 v[140:141], v[140:141], v[158:159] neg_lo:[0,1] neg_hi:[0,1]
	v_pk_add_f32 v[148:149], v[144:145], v[148:149] neg_lo:[0,1] neg_hi:[0,1]
	v_mov_b32_e32 v147, v155
	v_mov_b32_e32 v145, v143
	v_pk_add_f32 v[140:141], v[156:157], v[140:141] neg_lo:[0,1] neg_hi:[0,1]
	v_pk_add_f32 v[146:147], v[146:147], v[152:153] neg_lo:[0,1] neg_hi:[0,1]
	v_pk_add_f32 v[142:143], v[144:145], v[164:165] neg_lo:[0,1] neg_hi:[0,1]
	v_pk_add_f32 v[152:153], v[160:161], v[140:141]
	v_pk_add_f32 v[144:145], v[142:143], v[146:147]
	v_mov_b32_e32 v143, v141
	v_pk_add_f32 v[140:141], v[162:163], v[142:143]
	v_mov_b32_e32 v147, v161
	v_pk_add_f32 v[140:141], v[140:141], v[146:147] neg_lo:[0,1] neg_hi:[0,1]
	v_mov_b32_e32 v142, v144
	v_mov_b32_e32 v143, v153
	v_pk_add_f32 v[142:143], v[142:143], v[140:141] neg_lo:[0,1] neg_hi:[0,1]
	v_pk_add_f32 v[140:141], v[148:149], v[140:141] neg_lo:[0,1] neg_hi:[0,1]
	v_pk_add_f32 v[142:143], v[146:147], v[142:143] neg_lo:[0,1] neg_hi:[0,1]
	s_nop 0
	v_pk_add_f32 v[140:141], v[140:141], v[142:143]
	v_pk_add_f32 v[142:143], v[152:153], v[144:145]
	s_nop 0
	v_pk_add_f32 v[144:145], v[150:151], v[142:143]
	s_nop 0
	v_pk_add_f32 v[146:147], v[144:145], v[150:151] neg_lo:[0,1] neg_hi:[0,1]
	s_nop 0
	v_pk_add_f32 v[142:143], v[142:143], v[146:147] neg_lo:[0,1] neg_hi:[0,1]
	v_add_f32_e32 v147, v113, v133
	v_pk_add_f32 v[140:141], v[140:141], v[142:143]
	v_add_f32_e32 v142, v112, v132
	v_mul_f32_e64 v143, |v142|, s20
	v_pk_add_f32 v[140:141], v[144:145], v[140:141]
	v_fma_f32 v144, |v142|, s20, -v143
	v_rndne_f32_e32 v145, v143
	v_fma_f32 v144, |v142|, s51, v144
	v_sub_f32_e32 v143, v143, v145
	v_add_f32_e32 v143, v143, v144
	v_cndmask_b32_e32 v140, v221, v140, vcc
	v_cmp_neq_f32_e32 vcc, s77, v169
	v_exp_f32_e32 v143, v143
	v_cvt_i32_f32_e32 v144, v145
	v_cndmask_b32_e32 v141, v221, v141, vcc
	v_cmp_lt_f32_e64 vcc, |v169|, s79
	s_nop 1
	v_cndmask_b32_e32 v141, v141, v169, vcc
	v_cmp_lt_f32_e64 vcc, |v168|, s79
	s_nop 1
	v_cndmask_b32_e32 v140, v140, v168, vcc
	v_pk_add_f32 v[138:139], v[138:139], v[140:141] neg_lo:[0,1] neg_hi:[0,1]
	v_ldexp_f32 v141, v143, v144
	v_cmp_ngt_f32_e64 vcc, |v142|, s54
	v_min_f32_e32 v140, 0, v142
	s_nop 0
	v_cndmask_b32_e32 v141, 0, v141, vcc
	v_cmp_nlt_f32_e64 vcc, |v142|, s55
	s_nop 1
	v_cndmask_b32_e32 v185, v221, v141, vcc
	v_add_f32_e32 v144, 1.0, v185
	v_add_f32_e32 v141, -1.0, v144
	v_sub_f32_e32 v142, v141, v144
	v_add_f32_e32 v142, 1.0, v142
	v_sub_f32_e32 v141, v185, v141
	v_add_f32_e32 v145, v141, v142
	v_mul_f32_e64 v141, |v147|, s20
	v_fma_f32 v142, |v147|, s20, -v141
	v_rndne_f32_e32 v143, v141
	v_fma_f32 v142, |v147|, s51, v142
	v_sub_f32_e32 v141, v141, v143
	v_add_f32_e32 v141, v141, v142
	v_exp_f32_e32 v148, v141
	v_cvt_i32_f32_e32 v149, v143
	v_cvt_f64_f32_e32 v[142:143], v144
	v_frexp_exp_i32_f64_e32 v150, v[142:143]
	v_cmp_ngt_f32_e64 vcc, |v147|, s54
	v_ldexp_f32 v142, v148, v149
	v_min_f32_e32 v141, 0, v147
	v_cndmask_b32_e32 v142, 0, v142, vcc
	v_cmp_nlt_f32_e64 vcc, |v147|, s55
	v_frexp_mant_f32_e32 v146, v144
	s_nop 0
	v_cndmask_b32_e32 v186, v221, v142, vcc
	v_add_f32_e32 v147, 1.0, v186
	v_add_f32_e32 v142, -1.0, v147
	v_sub_f32_e32 v143, v142, v147
	v_add_f32_e32 v143, 1.0, v143
	v_sub_f32_e32 v142, v186, v142
	v_add_f32_e32 v148, v142, v143
	v_frexp_mant_f32_e32 v149, v147
	v_cvt_f64_f32_e32 v[142:143], v147
	v_frexp_exp_i32_f64_e32 v142, v[142:143]
	v_cmp_gt_f32_e32 vcc, s78, v149
	s_nop 1
	v_subbrev_co_u32_e32 v162, vcc, 0, v142, vcc
	v_cmp_gt_f32_e32 vcc, s78, v146
	s_nop 1
	v_subbrev_co_u32_e32 v163, vcc, 0, v150, vcc
	v_sub_u32_e32 v143, 0, v163
	v_ldexp_f32 v142, v144, v143
	v_ldexp_f32 v144, v145, v143
	v_sub_u32_e32 v145, 0, v162
	v_ldexp_f32 v143, v147, v145
	v_pk_add_f32 v[146:147], v[142:143], 1.0 op_sel_hi:[1,0]
	v_ldexp_f32 v145, v148, v145
	v_pk_add_f32 v[148:149], v[146:147], -1.0 op_sel_hi:[1,0]
	v_pk_add_f32 v[154:155], v[142:143], -1.0 op_sel_hi:[1,0]
	v_pk_add_f32 v[148:149], v[142:143], v[148:149] neg_lo:[0,1] neg_hi:[0,1]
; __device__ __forceinline__ void epi_all_run(const void* Pk_, int l, int s, const f32x4 (&acc)[2][2][4][2], const pg8::Unit& u, int wr, int wc, int fr, int fq) {
;     ...
;                         const int row = row0 + ai * 128 + m * 16;
;                         const f32x4 z = acc[ai][0][m][0] + fbv;
;                         f32x4 ls;
; #pragma unroll
;                         for (int j = 0; j < 4; ++j) ls[j] = fminf(z[j], 0.f) - log1pf(expf(-fabsf(z[j])));
;                         *(f32x4*)(logf + (size_t)row * 4) = ls;
	v_pk_add_f32 v[156:157], v[154:155], 1.0 op_sel_hi:[1,0]
	v_pk_add_f32 v[148:149], v[144:145], v[148:149]
	v_pk_add_f32 v[142:143], v[142:143], v[156:157] neg_lo:[0,1] neg_hi:[0,1]
	v_pk_add_f32 v[150:151], v[146:147], v[148:149]
	v_pk_add_f32 v[142:143], v[144:145], v[142:143]
	v_rcp_f32_e32 v152, v150
	v_rcp_f32_e32 v153, v151
	v_pk_add_f32 v[144:145], v[154:155], v[142:143]
	v_pk_add_f32 v[146:147], v[146:147], v[150:151] neg_lo:[0,1] neg_hi:[0,1]
	v_pk_add_f32 v[154:155], v[154:155], v[144:145] neg_lo:[0,1] neg_hi:[0,1]
	v_pk_add_f32 v[146:147], v[148:149], v[146:147]
	v_pk_mul_f32 v[148:149], v[144:145], v[152:153]
	v_pk_add_f32 v[142:143], v[142:143], v[154:155]
	v_pk_mul_f32 v[154:155], v[150:151], v[148:149]
	v_cmp_neq_f32_e32 vcc, s77, v185
	v_pk_fma_f32 v[156:157], v[148:149], v[150:151], v[154:155] neg_lo:[0,0,1] neg_hi:[0,0,1]
	s_nop 0
	v_pk_fma_f32 v[156:157], v[148:149], v[146:147], v[156:157]
	s_nop 0
	v_pk_add_f32 v[158:159], v[154:155], v[156:157]
	s_nop 0
	v_pk_add_f32 v[160:161], v[144:145], v[158:159] neg_lo:[0,1] neg_hi:[0,1]
	v_pk_add_f32 v[154:155], v[158:159], v[154:155] neg_lo:[0,1] neg_hi:[0,1]
	v_pk_add_f32 v[144:145], v[144:145], v[160:161] neg_lo:[0,1] neg_hi:[0,1]
	s_nop 0
	v_pk_add_f32 v[144:145], v[144:145], v[158:159] neg_lo:[0,1] neg_hi:[0,1]
	s_nop 0
	v_pk_add_f32 v[142:143], v[142:143], v[144:145]
	v_pk_add_f32 v[144:145], v[154:155], v[156:157] neg_lo:[0,1] neg_hi:[0,1]
	s_nop 0
	v_pk_add_f32 v[142:143], v[144:145], v[142:143]
	s_nop 0
	v_pk_add_f32 v[144:145], v[160:161], v[142:143]
	s_nop 0
	v_pk_mul_f32 v[154:155], v[152:153], v[144:145]
	s_nop 0
	v_pk_mul_f32 v[156:157], v[150:151], v[154:155]
	s_nop 0
	v_pk_fma_f32 v[150:151], v[154:155], v[150:151], v[156:157] neg_lo:[0,0,1] neg_hi:[0,0,1]
	s_nop 0
	v_pk_fma_f32 v[146:147], v[154:155], v[146:147], v[150:151]
	v_pk_add_f32 v[150:151], v[160:161], v[144:145] neg_lo:[0,1] neg_hi:[0,1]
	s_nop 0
	v_pk_add_f32 v[142:143], v[142:143], v[150:151]
	v_pk_add_f32 v[150:151], v[156:157], v[146:147]
	s_nop 0
	v_pk_add_f32 v[158:159], v[144:145], v[150:151] neg_lo:[0,1] neg_hi:[0,1]
	v_pk_add_f32 v[156:157], v[150:151], v[156:157] neg_lo:[0,1] neg_hi:[0,1]
	v_pk_add_f32 v[144:145], v[144:145], v[158:159] neg_lo:[0,1] neg_hi:[0,1]
	s_nop 0
	v_pk_add_f32 v[144:145], v[144:145], v[150:151] neg_lo:[0,1] neg_hi:[0,1]
	s_nop 0
	v_pk_add_f32 v[142:143], v[142:143], v[144:145]
	v_pk_add_f32 v[144:145], v[156:157], v[146:147] neg_lo:[0,1] neg_hi:[0,1]
	s_nop 0
	v_pk_add_f32 v[142:143], v[144:145], v[142:143]
	v_pk_add_f32 v[144:145], v[148:149], v[154:155]
	v_pk_add_f32 v[142:143], v[158:159], v[142:143]
	v_pk_add_f32 v[146:147], v[144:145], v[148:149] neg_lo:[0,1] neg_hi:[0,1]
	v_pk_mul_f32 v[142:143], v[152:153], v[142:143]
	v_pk_add_f32 v[146:147], v[154:155], v[146:147] neg_lo:[0,1] neg_hi:[0,1]
	v_cvt_f32_i32_e32 v149, v162
	v_pk_add_f32 v[142:143], v[146:147], v[142:143]
	v_cvt_f32_i32_e32 v148, v163
	v_pk_add_f32 v[146:147], v[144:145], v[142:143]
	v_pk_mul_f32 v[154:155], v[148:149], s[84:85] op_sel_hi:[1,0]
	v_pk_mul_f32 v[150:151], v[146:147], v[146:147]
	v_pk_add_f32 v[144:145], v[146:147], v[144:145] neg_lo:[0,1] neg_hi:[0,1]
	v_pk_fma_f32 v[152:153], v[150:151], s[80:81], v[134:135] op_sel_hi:[1,0,0]
	v_pk_add_f32 v[142:143], v[142:143], v[144:145] neg_lo:[0,1] neg_hi:[0,1]
	v_ldexp_f32 v144, v146, 1
	v_pk_fma_f32 v[152:153], v[150:151], v[152:153], s[82:83] op_sel_hi:[1,1,0]
	v_ldexp_f32 v145, v147, 1
	v_pk_mul_f32 v[146:147], v[146:147], v[150:151]
	v_pk_fma_f32 v[156:157], v[148:149], s[84:85], v[154:155] op_sel_hi:[1,0,1] neg_lo:[0,0,1] neg_hi:[0,0,1]
	v_pk_mul_f32 v[146:147], v[146:147], v[152:153]
	v_mov_b32_e32 v159, v145
	v_pk_add_f32 v[150:151], v[144:145], v[146:147]
	v_ldexp_f32 v142, v142, 1
	v_pk_add_f32 v[144:145], v[150:151], v[144:145] neg_lo:[0,1] neg_hi:[0,1]
	v_pk_fma_f32 v[148:149], v[148:149], s[86:87], v[156:157] op_sel_hi:[1,0,1]
; __device__ __forceinline__ void epi_all_run(const void* Pk_, int l, int s, const f32x4 (&acc)[2][2][4][2], const pg8::Unit& u, int wr, int wc, int fr, int fq) {
;     ...
;                         const int row = row0 + ai * 128 + m * 16;
;                         const f32x4 z = acc[ai][0][m][0] + fbv;
;                         f32x4 ls;
; #pragma unroll
;                         for (int j = 0; j < 4; ++j) ls[j] = fminf(z[j], 0.f) - log1pf(expf(-fabsf(z[j])));
;                         *(f32x4*)(logf + (size_t)row * 4) = ls;
	v_ldexp_f32 v143, v143, 1
	v_pk_add_f32 v[144:145], v[146:147], v[144:145] neg_lo:[0,1] neg_hi:[0,1]
	v_mov_b32_e32 v152, v154
	v_mov_b32_e32 v153, v147
	v_mov_b32_e32 v158, v148
	v_pk_add_f32 v[146:147], v[142:143], v[144:145]
	v_mov_b32_e32 v144, v154
	v_mov_b32_e32 v142, v148
	v_pk_add_f32 v[152:153], v[152:153], v[158:159]
	v_pk_add_f32 v[158:159], v[144:145], v[142:143]
	v_mov_b32_e32 v142, v150
	v_mov_b32_e32 v144, v146
	v_pk_add_f32 v[156:157], v[154:155], v[148:149]
	v_pk_add_f32 v[142:143], v[142:143], v[144:145]
	v_pk_add_f32 v[144:145], v[150:151], v[146:147]
	v_mov_b32_e32 v160, v156
	v_mov_b32_e32 v161, v155
	v_mov_b32_e32 v162, v144
	v_mov_b32_e32 v163, v149
	v_pk_add_f32 v[142:143], v[152:153], v[142:143]
	v_pk_add_f32 v[152:153], v[156:157], v[144:145]
	v_pk_add_f32 v[164:165], v[160:161], v[162:163]
	v_mov_b32_e32 v166, v144
	v_mov_b32_e32 v167, v153
	v_mov_b32_e32 v168, v150
	v_mov_b32_e32 v169, v157
	v_pk_add_f32 v[160:161], v[164:165], v[160:161] neg_lo:[0,1] neg_hi:[0,1]
	v_pk_add_f32 v[166:167], v[166:167], v[168:169] neg_lo:[0,1] neg_hi:[0,1]
	v_pk_add_f32 v[164:165], v[156:157], v[154:155] neg_lo:[0,1] neg_hi:[0,1]
	v_pk_add_f32 v[162:163], v[162:163], v[160:161] neg_lo:[0,1] neg_hi:[0,1]
	v_mov_b32_e32 v168, v156
	v_mov_b32_e32 v169, v153
	v_mov_b32_e32 v155, v167
	v_mov_b32_e32 v161, v151
	v_pk_add_f32 v[150:151], v[144:145], v[150:151] neg_lo:[0,1] neg_hi:[0,1]
	v_pk_add_f32 v[154:155], v[168:169], v[154:155] neg_lo:[0,1] neg_hi:[0,1]
	v_pk_add_f32 v[164:165], v[148:149], v[164:165] neg_lo:[0,1] neg_hi:[0,1]
	v_pk_add_f32 v[142:143], v[142:143], v[160:161] neg_lo:[0,1] neg_hi:[0,1]
	v_pk_add_f32 v[150:151], v[146:147], v[150:151] neg_lo:[0,1] neg_hi:[0,1]
	v_mov_b32_e32 v149, v157
	v_mov_b32_e32 v147, v145
	v_pk_add_f32 v[142:143], v[158:159], v[142:143] neg_lo:[0,1] neg_hi:[0,1]
	v_pk_add_f32 v[148:149], v[148:149], v[154:155] neg_lo:[0,1] neg_hi:[0,1]
	v_pk_add_f32 v[144:145], v[146:147], v[166:167] neg_lo:[0,1] neg_hi:[0,1]
	v_pk_add_f32 v[154:155], v[162:163], v[142:143]
	v_pk_add_f32 v[146:147], v[144:145], v[148:149]
	v_mov_b32_e32 v145, v143
	v_pk_add_f32 v[142:143], v[164:165], v[144:145]
	v_mov_b32_e32 v149, v163
	v_pk_add_f32 v[142:143], v[142:143], v[148:149] neg_lo:[0,1] neg_hi:[0,1]
	v_mov_b32_e32 v144, v146
	v_mov_b32_e32 v145, v155
	v_pk_add_f32 v[144:145], v[144:145], v[142:143] neg_lo:[0,1] neg_hi:[0,1]
	v_pk_add_f32 v[142:143], v[150:151], v[142:143] neg_lo:[0,1] neg_hi:[0,1]
	v_pk_add_f32 v[144:145], v[148:149], v[144:145] neg_lo:[0,1] neg_hi:[0,1]
	s_nop 0
	v_pk_add_f32 v[142:143], v[142:143], v[144:145]
	v_pk_add_f32 v[144:145], v[154:155], v[146:147]
	s_nop 0
	v_pk_add_f32 v[146:147], v[152:153], v[144:145]
	s_nop 0
	v_pk_add_f32 v[148:149], v[146:147], v[152:153] neg_lo:[0,1] neg_hi:[0,1]
	s_nop 0
	v_pk_add_f32 v[144:145], v[144:145], v[148:149] neg_lo:[0,1] neg_hi:[0,1]
	s_nop 0
	v_pk_add_f32 v[142:143], v[142:143], v[144:145]
	v_add_f32_e32 v144, v94, v130
	v_pk_add_f32 v[142:143], v[146:147], v[142:143]
	v_mul_f32_e64 v145, |v144|, s20
	v_cndmask_b32_e32 v142, v221, v142, vcc
	v_cmp_neq_f32_e32 vcc, s77, v186
	v_fma_f32 v146, |v144|, s20, -v145
	v_rndne_f32_e32 v147, v145
	v_cndmask_b32_e32 v143, v221, v143, vcc
	v_cmp_lt_f32_e64 vcc, |v186|, s79
	v_fma_f32 v146, |v144|, s51, v146
	v_sub_f32_e32 v145, v145, v147
	v_cndmask_b32_e32 v143, v143, v186, vcc
	v_cmp_lt_f32_e64 vcc, |v185|, s79
	v_add_f32_e32 v145, v145, v146
	v_exp_f32_e32 v145, v145
	v_cndmask_b32_e32 v142, v142, v185, vcc
	v_cvt_i32_f32_e32 v146, v147
	v_pk_add_f32 v[140:141], v[140:141], v[142:143] neg_lo:[0,1] neg_hi:[0,1]
	v_or_b32_e32 v142, 16, v184
	v_ashrrev_i32_e32 v143, 31, v142
	v_lshl_add_u64 v[142:143], v[142:143], 4, s[52:53]
	global_store_dwordx4 v[142:143], v[138:141], off
	s_branch .LBB0_76
.LBB0_76:
	s_or_b64 exec, exec, s[46:47]
	s_mov_b64 s[46:47], 0
